# forgetting attention: the tile-skip bound's decay-prefix loads are issued with the row-norm loads behind one wait; dilated bias-table build reads the table pointer once
# baseline (speedup 1.0000x reference)
; __global__ void __launch_bounds__(NTHR, 2) fwd_mega(Args args) {
;     ...
;                     { const int NTf = 4 * (qb + 1); const float* cg = C2 + (size_t)bh * SEQ; const float* og = OFFS + (size_t)(bh >> 3) * 64 * 8 + (bh & 7);
;                       const float* qn = NRM + bh * 128 + 4 * qb; const float* kn = NRM + 4096 + bh * 128;
;                       const float Qn = fmaxf(fmaxf(qn[0], qn[1]), fmaxf(qn[2], qn[3])) * 1.01f;
;                       const int t0_ = lane, t1_ = lane + 64;
;                       const float k0_ = (t0_ < NTf) ? kn[t0_] : 0.f, k1_ = (t1_ < NTf) ? kn[t1_] : 0.f;
;                       float kmax = fmaxf(k0_, k1_);
; #pragma unroll
;                       for (int o = 1; o < 64; o <<= 1) kmax = fmaxf(kmax, __shfl_xor(kmax, o));
;                       kmax *= 1.01f;
;                       const int q0_ = 256 * qb; const float Cq = cg[q0_] + og[(q0_ >> 7) * 8];
;                       const float thr = -Qn * kmax - 150.f;
;                       bool keep0 = true, keep1 = true;
;                       if (t0_ < NTf) { const int e = 64 * t0_ + 63; keep0 = !(Qn * k0_ * 1.01f + (Cq - (cg[e] + og[(e >> 7) * 8])) < thr); }
;                       if (t1_ < NTf) { const int e = 64 * t1_ + 63; keep1 = !(Qn * k1_ * 1.01f + (Cq - (cg[e] + og[(e >> 7) * 8])) < thr); }
;                       const unsigned long long b0 = __ballot(keep0), b1 = __ballot(keep1);
;                       const int first = b0 ? __builtin_ctzll(b0) : 64 + (b1 ? __builtin_ctzll(b1) : 0);
;                       ts = first & ~1; if (ts > NTf - 4) ts = NTf - 4; if (ts < 0) ts = 0;
;                       ts = __builtin_amdgcn_readfirstlane(ts); }
.LBB0_294:
	s_mov_b64 s[14:15], -1
	s_and_b64 vcc, exec, s[10:11]
	s_cbranch_vccz .LBB0_284
	s_lshl_b32 s10, s8, 7
	s_lshl_b32 s22, s12, 2
	s_ashr_i32 s11, s10, 31
	s_add_i32 s9, s22, 4
	s_lshl_b64 s[10:11], s[10:11], 2
	v_readlane_b32 s14, v255, 7
	v_readlane_b32 s15, v255, 8
	s_add_u32 s13, s14, s10
	s_mov_b32 s23, s31
	s_addc_u32 s16, s15, s11
	s_lshl_b64 s[14:15], s[22:23], 2
	s_add_u32 s14, s13, s14
	s_addc_u32 s15, s16, s15
	global_load_dwordx4 v[2:5], v1, s[14:15]
	s_ashr_i32 s99, s8, 31
	s_mov_b32 s98, s8
	s_lshl_b64 s[98:99], s[98:99], 15
	v_readlane_b32 s100, v255, 1
	v_readlane_b32 s101, v255, 2
	s_nop 0
	s_add_u32 s98, s100, s98
	s_addc_u32 s99, s101, s99
	s_ashr_i32 s100, s8, 3
	s_ashr_i32 s101, s100, 31
	s_lshl_b64 s[100:101], s[100:101], 11
	s_add_u32 s100, s24, s100
	s_addc_u32 s101, s25, s101
	s_and_b32 vcc_lo, s8, 7
	s_lshl_b32 vcc_lo, vcc_lo, 2
	s_add_u32 s100, s100, vcc_lo
	s_addc_u32 s101, s101, 0
	v_mov_b32_e32 v116, s12
	v_lshlrev_b32_e32 v117, 10, v116
	v_lshlrev_b32_e32 v118, 6, v116
	global_load_dword v114, v117, s[98:99]
	global_load_dword v115, v118, s[100:101]
	s_add_u32 s10, s6, s10
	s_addc_u32 s11, s7, s11
	v_cmp_gt_u32_e64 s[40:41], s9, v226
	v_mov_b32_e32 v0, 0
	v_lshlrev_b32_e32 v7, 2, v226
	v_mov_b32_e32 v6, 0
	s_and_saveexec_b64 s[14:15], s[40:41]
	s_cbranch_execz .LBB0_297
	global_load_dword v6, v7, s[10:11]
	global_load_dword v110, v249, s[98:99] offset:252
	global_load_dword v111, v250, s[100:101]
.LBB0_297:
	s_or_b64 exec, exec, s[14:15]
	v_cmp_gt_u32_e32 vcc, s9, v248
	s_and_saveexec_b64 s[14:15], vcc
	s_cbranch_execz .LBB0_299
	global_load_dword v0, v7, s[10:11] offset:256
	global_load_dword v112, v251, s[98:99] offset:252
	global_load_dword v113, v252, s[100:101]
.LBB0_299:
	s_or_b64 exec, exec, s[14:15]
	s_waitcnt vmcnt(0)
	v_max_f32_e32 v5, v5, v5
	v_max_f32_e32 v4, v4, v4
	v_max_f32_e32 v4, v4, v5
	v_max3_f32 v2, v2, v3, v4
	v_max_f32_e32 v3, v0, v0
	v_max_f32_e32 v4, v6, v6
	v_max_f32_e32 v3, v4, v3
	v_add_u32_e32 v4, 64, v236
	v_xor_b32_e32 v5, 1, v235
	v_cmp_lt_i32_e64 s[42:43], v5, v4
	s_ashr_i32 s9, s8, 31
	s_lshl_b64 s[10:11], s[8:9], 15
	v_cndmask_b32_e64 v5, v235, v5, s[42:43]
	v_lshlrev_b32_e32 v5, 2, v5
	ds_bpermute_b32 v5, v5, v3
	v_readlane_b32 s14, v255, 1
	v_readlane_b32 s15, v255, 2
	s_add_u32 s16, s14, s10
	s_addc_u32 s17, s15, s11
	s_waitcnt lgkmcnt(0)
	v_max_f32_e32 v5, v5, v5
	v_max_f32_e32 v3, v3, v5
	v_xor_b32_e32 v5, 2, v235
	v_cmp_lt_i32_e64 s[42:43], v5, v4
	s_ashr_i32 s14, s8, 3
	s_ashr_i32 s15, s14, 31
	v_cndmask_b32_e64 v5, v235, v5, s[42:43]
	v_lshlrev_b32_e32 v5, 2, v5
	ds_bpermute_b32 v5, v5, v3
	s_lshl_b64 s[10:11], s[14:15], 11
	s_add_u32 s9, s24, s10
	s_addc_u32 s10, s25, s11
	s_and_b32 s23, s8, 7
	s_waitcnt lgkmcnt(0)
	v_max_f32_e32 v5, v5, v5
	v_max_f32_e32 v3, v3, v5
	v_xor_b32_e32 v5, 4, v235
	v_cmp_lt_i32_e64 s[42:43], v5, v4
	s_lshl_b32 s8, s23, 2
	s_add_u32 s26, s9, s8
	v_cndmask_b32_e64 v5, v235, v5, s[42:43]
	v_lshlrev_b32_e32 v5, 2, v5
	ds_bpermute_b32 v5, v5, v3
	s_addc_u32 s27, s10, 0
	s_lshl_b32 s30, s12, 8
	s_lshl_b64 s[8:9], s[30:31], 2
	s_add_u32 s8, s16, s8
	s_waitcnt lgkmcnt(0)
	v_max_f32_e32 v5, v5, v5
	v_max_f32_e32 v3, v3, v5
	v_xor_b32_e32 v5, 8, v235
	v_cmp_lt_i32_e64 s[42:43], v5, v4
	s_addc_u32 s9, s17, s9
	v_mul_f32_e32 v2, 0x3f8147ae, v2
	v_cndmask_b32_e64 v5, v235, v5, s[42:43]
	v_lshlrev_b32_e32 v5, 2, v5
	ds_bpermute_b32 v5, v5, v3
	s_mov_b64 s[10:11], -1
	s_waitcnt lgkmcnt(0)
	v_max_f32_e32 v5, v5, v5
	v_max_f32_e32 v3, v3, v5
	v_xor_b32_e32 v5, 16, v235
	v_cmp_lt_i32_e64 s[42:43], v5, v4
	s_nop 1
	v_cndmask_b32_e64 v5, v235, v5, s[42:43]
	v_lshlrev_b32_e32 v5, 2, v5
	ds_bpermute_b32 v5, v5, v3
	s_waitcnt lgkmcnt(0)
	v_max_f32_e32 v5, v5, v5
	v_max_f32_e32 v3, v3, v5
	v_xor_b32_e32 v5, 32, v235
	v_cmp_lt_i32_e64 s[42:43], v5, v4
	s_nop 1
	v_cndmask_b32_e64 v4, v235, v5, s[42:43]
	v_lshlrev_b32_e32 v4, 2, v4
	ds_bpermute_b32 v4, v4, v3
	s_waitcnt lgkmcnt(0)
	v_max_f32_e32 v4, v4, v4
	v_max_f32_e32 v3, v3, v4
	v_mul_f32_e32 v4, 0x3f8147ae, v3
	s_lshl_b32 s8, s12, 4
	s_mov_b32 s9, s31
	s_lshl_b64 s[8:9], s[8:9], 2
	s_add_u32 s8, s26, s8
	s_addc_u32 s9, s27, s9
	s_mov_b32 s8, 0xc3160000
	v_fma_f32 v4, -v2, v4, s8
	s_mov_b64 s[8:9], -1
	v_add_f32_e32 v3, v114, v115
	s_and_saveexec_b64 s[42:43], s[40:41]
	s_cbranch_execz .LBB0_301
	v_mul_f32_e32 v6, v2, v6
	v_add_f32_e32 v5, v110, v111
	v_sub_f32_e32 v5, v3, v5
	v_fmac_f32_e32 v5, 0x3f8147ae, v6
	v_cmp_nlt_f32_e64 s[40:41], v5, v4
	s_orn2_b64 s[10:11], s[40:41], exec
.LBB0_301:
	s_or_b64 exec, exec, s[42:43]
	s_and_saveexec_b64 s[40:41], vcc
	s_cbranch_execz .LBB0_303
	v_mul_f32_e32 v0, v2, v0
	v_add_f32_e32 v2, v112, v113
	v_sub_f32_e32 v2, v3, v2
	v_fmac_f32_e32 v2, 0x3f8147ae, v0
	v_cmp_nlt_f32_e32 vcc, v2, v4
	s_orn2_b64 s[8:9], vcc, exec

; #define LAS __attribute__((address_space(3)))
; __global__ void __launch_bounds__(NTHR, 2) fwd_mega(Args args) {
;     ...
;                 for (int e = tid; e < 36 * 192; e += NTHR) { const int tb_ = e / 192, st_ = e - 192 * tb_ - 32, p_ = tb_ / 12, h_ = tb_ - 12 * p_, r_ = (p_ == 0) ? 1 : (p_ == 1 ? 4 : 16); float tv = -INFINITY;
;                     if (st_ >= 0 && st_ <= 128) { const int dist = st_ * r_; int bk;
;                         if (dist < 16) bk = dist; else { bk = 16 + (int)(logf((float)dist * (1.f / 16.f)) / logf(128.f) * 16.f); bk = bk > 31 ? 31 : bk; }
;                         tv = ap->in[I_REL][bk * 12 + h_] * LOG2E; }
;                     ((LAS float*)(lds + DIL_TBLS))[e] = tv; }
.LBB0_498:
	s_movk_i32 s4, 0x1b00
	v_cmp_gt_i32_e32 vcc, s4, v247
	s_and_saveexec_b64 s[8:9], vcc
	s_cbranch_execz .LBB0_505
	s_load_dwordx2 s[100:101], s[82:83], 0x10
	s_add_i32 s4, 0, 0x1b000
	s_waitcnt lgkmcnt(0)
	v_lshl_add_u32 v2, v247, 2, s4
	s_mov_b64 s[10:11], 0
	v_mov_b32_e32 v3, v247
	s_branch .LBB0_502
.LBB0_500:
	s_or_b64 exec, exec, s[14:15]
	s_mov_b32 s4, 0xc71c71c7
	v_mul_hi_i32 v5, v3, s4
	v_lshrrev_b32_e32 v6, 31, v5
	v_ashrrev_i32_e32 v5, 9, v5
	v_add3_u32 v4, v5, v6, v4
	v_mad_u64_u32 v[4:5], s[6:7], v4, 12, v[0:1]
	v_ashrrev_i32_e32 v5, 31, v4
	v_lshl_add_u64 v[4:5], v[4:5], 2, s[100:101]
	global_load_dword v0, v[4:5], off
	s_waitcnt vmcnt(0)
	v_mul_f32_e32 v5, 0x3fb8aa3b, v0
